# v58 + the 32 context-chunk SGU items run in the transposition phase on WGs 224..255 (their tiles move to WGs 16..47): even mixer has two SGU rounds instead of three
# speedup vs baseline: 1.0157x; 1.0066x over previous
.LBB0_245:
	s_add_i32 s2, s2, s56
	s_and_b32 s98, s62, 7
	s_movk_i32 s99, 0x41f
	s_cmp_eq_u32 s98, 4
	s_cselect_b32 s98, s99, 0x3ff
	s_cmp_eq_u32 s56, 0x100
	s_cselect_b32 s98, s98, s99
	s_cmp_gt_i32 s2, s98
	s_nop 0
	s_nop 0
	s_nop 0
	s_nop 0
	s_nop 0
	s_nop 0
	s_nop 0
	s_nop 0
	s_cbranch_scc1 .LBB0_338

.Ltr_phase:
	s_load_dwordx2 s[64:65], s[72:73], 0x120
	v_and_b32_e32 v2, 7, v208
	v_bfe_u32 v3, v208, 3, 3
	v_lshrrev_b32_e32 v0, 6, v208
	s_nop 0
	v_readfirstlane_b32 s84, v0
	v_mul_u32_u24_e32 v4, 0x11000, v3
	v_lshl_add_u32 v4, v2, 4, v4
	v_lshlrev_b32_e32 v5, 11, v3
	v_lshl_add_u32 v5, v2, 4, v5
	s_mul_i32 s38, s84, 8448
	v_mul_u32_u24_e32 v6, 1056, v2
	v_lshl_add_u32 v6, v3, 1, v6
	v_add_u32_e32 v6, s38, v6
	v_mul_u32_u24_e32 v7, 132, v3
	v_lshl_add_u32 v7, v2, 4, v7
	v_add_u32_e32 v7, s38, v7
	s_mul_i32 s98, s84, 0x440000
	s_lshl_b32 s99, s84, 7
	s_mov_b32 s38, s96
	s_waitcnt lgkmcnt(0)
	s_cmp_eq_u32 s56, 0x100
	s_cbranch_scc0 .Ltr_loop
	s_cmp_lt_u32 s96, 0xe0
	s_cbranch_scc1 .Ltr_loop
	s_mov_b64 s[0:1], s[72:73]
	s_add_i32 s2, s96, 0x320
	s_branch .LBB0_246
.Ltr_loop:
	s_cmpk_ge_u32 s38, 0x110
	s_cbranch_scc1 .Ltr_done
	s_lshl_b32 s100, s38, 7
	s_add_u32 s100, s100, s98
	s_add_u32 s100, s100, 0x6d00000
	s_add_u32 s2, s64, s100
	s_addc_u32 s3, s65, 0
	s_lshl_b32 s100, s38, 17
	s_add_u32 s100, s100, s99
	s_add_u32 s100, s100, 0xed00000
	s_add_u32 s6, s64, s100
	s_addc_u32 s7, s65, 0
	v_mov_b32_e32 v8, v4
	global_load_dwordx4 v[16:19], v8, s[2:3]
	v_add_u32_e32 v8, 0x88000, v8
	global_load_dwordx4 v[20:23], v8, s[2:3]
	v_add_u32_e32 v8, 0x88000, v8
	global_load_dwordx4 v[24:27], v8, s[2:3]
	v_add_u32_e32 v8, 0x88000, v8
	global_load_dwordx4 v[28:31], v8, s[2:3]
	v_add_u32_e32 v8, 0x88000, v8
	global_load_dwordx4 v[32:35], v8, s[2:3]
	v_add_u32_e32 v8, 0x88000, v8
	global_load_dwordx4 v[36:39], v8, s[2:3]
	v_add_u32_e32 v8, 0x88000, v8
	global_load_dwordx4 v[40:43], v8, s[2:3]
	v_add_u32_e32 v8, 0x88000, v8
	global_load_dwordx4 v[44:47], v8, s[2:3]
	s_waitcnt vmcnt(7)
	ds_write_b16 v6, v16 offset:0
	ds_write_b16_d16_hi v6, v16 offset:132
	ds_write_b16 v6, v17 offset:264
	ds_write_b16_d16_hi v6, v17 offset:396
	ds_write_b16 v6, v18 offset:528
	ds_write_b16_d16_hi v6, v18 offset:660
	ds_write_b16 v6, v19 offset:792
	ds_write_b16_d16_hi v6, v19 offset:924
	s_waitcnt vmcnt(6)
	ds_write_b16 v6, v20 offset:16
	ds_write_b16_d16_hi v6, v20 offset:148
	ds_write_b16 v6, v21 offset:280
	ds_write_b16_d16_hi v6, v21 offset:412
	ds_write_b16 v6, v22 offset:544
	ds_write_b16_d16_hi v6, v22 offset:676
	ds_write_b16 v6, v23 offset:808
	ds_write_b16_d16_hi v6, v23 offset:940
	s_waitcnt vmcnt(5)
	ds_write_b16 v6, v24 offset:32
	ds_write_b16_d16_hi v6, v24 offset:164
	ds_write_b16 v6, v25 offset:296
	ds_write_b16_d16_hi v6, v25 offset:428
	ds_write_b16 v6, v26 offset:560
	ds_write_b16_d16_hi v6, v26 offset:692
	ds_write_b16 v6, v27 offset:824
	ds_write_b16_d16_hi v6, v27 offset:956
	s_waitcnt vmcnt(4)
	ds_write_b16 v6, v28 offset:48
	ds_write_b16_d16_hi v6, v28 offset:180
	ds_write_b16 v6, v29 offset:312
	ds_write_b16_d16_hi v6, v29 offset:444
	ds_write_b16 v6, v30 offset:576
	ds_write_b16_d16_hi v6, v30 offset:708
	ds_write_b16 v6, v31 offset:840
	ds_write_b16_d16_hi v6, v31 offset:972
	s_waitcnt vmcnt(3)
	ds_write_b16 v6, v32 offset:64
	ds_write_b16_d16_hi v6, v32 offset:196
	ds_write_b16 v6, v33 offset:328
	ds_write_b16_d16_hi v6, v33 offset:460
	ds_write_b16 v6, v34 offset:592
	ds_write_b16_d16_hi v6, v34 offset:724
	ds_write_b16 v6, v35 offset:856
	ds_write_b16_d16_hi v6, v35 offset:988
	s_waitcnt vmcnt(2)
	ds_write_b16 v6, v36 offset:80
	ds_write_b16_d16_hi v6, v36 offset:212
	ds_write_b16 v6, v37 offset:344
	ds_write_b16_d16_hi v6, v37 offset:476
	ds_write_b16 v6, v38 offset:608
	ds_write_b16_d16_hi v6, v38 offset:740
	ds_write_b16 v6, v39 offset:872
	ds_write_b16_d16_hi v6, v39 offset:1004
	s_waitcnt vmcnt(1)
	ds_write_b16 v6, v40 offset:96
	ds_write_b16_d16_hi v6, v40 offset:228
	ds_write_b16 v6, v41 offset:360
	ds_write_b16_d16_hi v6, v41 offset:492
	ds_write_b16 v6, v42 offset:624
	ds_write_b16_d16_hi v6, v42 offset:756
	ds_write_b16 v6, v43 offset:888
	ds_write_b16_d16_hi v6, v43 offset:1020
	s_waitcnt vmcnt(0)
	ds_write_b16 v6, v44 offset:112
	ds_write_b16_d16_hi v6, v44 offset:244
	ds_write_b16 v6, v45 offset:376
	ds_write_b16_d16_hi v6, v45 offset:508
	ds_write_b16 v6, v46 offset:640
	ds_write_b16_d16_hi v6, v46 offset:772
	ds_write_b16 v6, v47 offset:904
	ds_write_b16_d16_hi v6, v47 offset:1036
	ds_read_b32 v48, v7 offset:0
	ds_read_b32 v49, v7 offset:4
	ds_read_b32 v50, v7 offset:8
	ds_read_b32 v51, v7 offset:12
	ds_read_b32 v52, v7 offset:1056
	ds_read_b32 v53, v7 offset:1060
	ds_read_b32 v54, v7 offset:1064
	ds_read_b32 v55, v7 offset:1068
	ds_read_b32 v56, v7 offset:2112
	ds_read_b32 v57, v7 offset:2116
	ds_read_b32 v58, v7 offset:2120
	ds_read_b32 v59, v7 offset:2124
	ds_read_b32 v60, v7 offset:3168
	ds_read_b32 v61, v7 offset:3172
	ds_read_b32 v62, v7 offset:3176
	ds_read_b32 v63, v7 offset:3180
	ds_read_b32 v64, v7 offset:4224
	ds_read_b32 v65, v7 offset:4228
	ds_read_b32 v66, v7 offset:4232
	ds_read_b32 v67, v7 offset:4236
	ds_read_b32 v68, v7 offset:5280
	ds_read_b32 v69, v7 offset:5284
	ds_read_b32 v70, v7 offset:5288
	ds_read_b32 v71, v7 offset:5292
	ds_read_b32 v72, v7 offset:6336
	ds_read_b32 v73, v7 offset:6340
	ds_read_b32 v74, v7 offset:6344
	ds_read_b32 v75, v7 offset:6348
	ds_read_b32 v76, v7 offset:7392
	ds_read_b32 v77, v7 offset:7396
	ds_read_b32 v78, v7 offset:7400
	ds_read_b32 v79, v7 offset:7404
	v_mov_b32_e32 v8, v5
	s_waitcnt lgkmcnt(0)
	global_store_dwordx4 v8, v[48:51], s[6:7]
	v_add_u32_e32 v8, 0x4000, v8
	global_store_dwordx4 v8, v[52:55], s[6:7]
	v_add_u32_e32 v8, 0x4000, v8
	global_store_dwordx4 v8, v[56:59], s[6:7]
	v_add_u32_e32 v8, 0x4000, v8
	global_store_dwordx4 v8, v[60:63], s[6:7]
	v_add_u32_e32 v8, 0x4000, v8
	global_store_dwordx4 v8, v[64:67], s[6:7]
	v_add_u32_e32 v8, 0x4000, v8
	global_store_dwordx4 v8, v[68:71], s[6:7]
	v_add_u32_e32 v8, 0x4000, v8
	global_store_dwordx4 v8, v[72:75], s[6:7]
	v_add_u32_e32 v8, 0x4000, v8
	global_store_dwordx4 v8, v[76:79], s[6:7]
	s_cmp_eq_u32 s56, 0x100
	s_cbranch_scc1 .Ltr_next256
	s_add_i32 s38, s38, s56
	s_waitcnt lgkmcnt(0)
	s_branch .Ltr_loop
.Ltr_next256:
	s_waitcnt lgkmcnt(0)
	s_cmp_ge_u32 s38, 0xe0
	s_cbranch_scc1 .Ltr_done
	s_add_i32 s38, s96, 0x100
	s_cmp_lt_u32 s96, 16
	s_cbranch_scc1 .Ltr_loop
	s_add_i32 s38, s96, 0xd0
	s_cmp_lt_u32 s96, 48
	s_cbranch_scc1 .Ltr_loop
	s_branch .Ltr_done
